# GQA attention loop: K/V tile loads use SGPR base + 32-bit per-lane offsets (no 64-bit address VALU per tile)
# speedup vs baseline: 1.0025x; 1.0025x over previous
; DI int TIDX() { int t = threadIdx.x; asm volatile("" : "+v"(t)); return t; }
; template <int DK, bool MLA>
; DI void attn_item(const h16* __restrict__ Q, const h16* __restrict__ Kp, const h16* __restrict__ Kr, const h16* __restrict__ Vt,
;                   int kbeg, int kend, h16* __restrict__ out, h16* sm) {
;     ...
;   const int tid = TIDX(), lane = tid & 63, w = tid >> 6, r = lane & 31, hh = lane >> 5;
;   h16x8 qf[DK / 16];
;   {
;     const h16* qr = Q + (size_t)(w * 32 + r) * DK + hh * 8;
; #pragma unroll
;     for (int ks = 0; ks < DK / 16; ++ks) qf[ks] = *(const h16x8*)(qr + ks * 16);
;   }
;   f32x16 ot[2];
; #pragma unroll
;   for (int i = 0; i < 16; ++i) { ot[0][i] = 0.f; ot[1][i] = 0.f; }
;   float m = -1000.f, lsum = 0.f;
;   u32x4 rkA[NCH], rvA[2], rkB[NCH], rvB[2];
;     ...
;   const int ntile = (kend - kbeg) >> 6;
;   ATT_GLOAD(rkA, rvA, kbeg)
;   ATT_GLOAD(rkB, rvB, kbeg + 64)
;   auto tile = [&](int it, u32x4 (&RK)[NCH], u32x4 (&RV)[2]) {
;     h16* ksm = sm + (it & 1) * BUF;
;     h16* vsm = ksm + 64 * KS;
; #pragma unroll
;     for (int i = 0; i < NCH; ++i) {
;       const int c = tid + 256 * i, key = c / NKC, part = c % NKC;
;       *(u32x4*)(ksm + key * KS + part * 8) = RK[i];
;     }
; #pragma unroll
;     for (int i = 0; i < 2; ++i) {
;       const int c = tid + 256 * i, dv = c >> 3, kc = c & 7;
;       *(u32x4*)(vsm + dv * 72 + kc * 8) = RV[i];
;     }
;     __syncthreads();
;     if (it + 2 < ntile) ATT_GLOAD(RK, RV, kbeg + (it + 2) * 64)
.LBB0_2732:
	s_and_b32 s53, s27, 7
	s_or_b32 s11, s53, s13
	s_mov_b64 s[8:9], -1
	s_andn2_b64 vcc, exec, s[6:7]
	s_mul_i32 s27, s11, 0x1100
	s_cbranch_vccz .LBB0_2744
	v_mov_b32_e32 v12, v203
	s_add_i32 s6, s27, s10
	s_mov_b32 s7, s37
	s_movk_i32 s2, 0xffe0
	v_ashrrev_i32_e32 v0, 1, v12
	s_lshl_b64 s[6:7], s[6:7], 7
	s_waitcnt vmcnt(4)
	v_bfi_b32 v144, s2, v0, v12
	s_add_u32 s8, s21, s6
	s_waitcnt vmcnt(2)
	v_ashrrev_i32_e32 v145, 31, v144
	s_addc_u32 s9, s22, s7
	v_bfe_u32 v13, v12, 5, 1
	v_lshlrev_b64 v[2:3], 7, v[144:145]
	v_lshl_add_u64 v[2:3], s[8:9], 0, v[2:3]
	v_lshlrev_b32_e32 v0, 4, v13
	s_lshr_b32 s6, s53, 2
	v_lshl_add_u64 v[2:3], v[2:3], 0, v[0:1]
	s_or_b32 s6, s6, s14
	global_load_dwordx4 v[80:83], v[2:3], off
	global_load_dwordx4 v[84:87], v[2:3], off offset:32
	global_load_dwordx4 v[88:91], v[2:3], off offset:64
	global_load_dwordx4 v[92:95], v[2:3], off offset:96
	v_ashrrev_i32_e32 v2, 31, v12
	s_mul_i32 s38, s6, 0x88000
	v_lshrrev_b32_e32 v2, 29, v2
	v_add_u32_e32 v10, 0x100, v12
	s_add_u32 s6, s23, s38
	v_add_u32_e32 v8, v12, v2
	v_ashrrev_i32_e32 v2, 31, v10
	s_addc_u32 s7, s24, 0
	v_lshrrev_b32_e32 v2, 29, v2
	s_add_u32 s38, s25, s38
	v_add_u32_e32 v4, v10, v2
	s_addc_u32 s39, s48, 0
	v_ashrrev_i32_e32 v15, 3, v4
	s_or_b32 s9, s26, 64
	v_and_b32_e32 v4, -8, v4
	v_ashrrev_i32_e32 v14, 3, v8
	v_add_u32_e32 v2, s9, v15
	v_sub_u32_e32 v16, v10, v4
	v_and_b32_e32 v8, -8, v8
	s_sub_i32 s8, 0x1100, s26
	v_ashrrev_i32_e32 v3, 31, v2
	v_lshlrev_b32_e32 v4, 3, v16
	v_add_u32_e32 v6, s9, v14
	v_sub_u32_e32 v17, v12, v8
	s_lshr_b32 s8, s8, 6
	v_lshlrev_b64 v[2:3], 7, v[2:3]
	v_ashrrev_i32_e32 v5, 31, v4
	v_ashrrev_i32_e32 v7, 31, v6
	v_lshlrev_b32_e32 v8, 3, v17
	s_lshl_b32 s9, s26, 1
	v_lshl_add_u64 v[2:3], s[6:7], 0, v[2:3]
	v_lshlrev_b64 v[4:5], 1, v[4:5]
	v_lshlrev_b64 v[6:7], 7, v[6:7]
	v_ashrrev_i32_e32 v9, 31, v8
	s_add_u32 s38, s38, s9
	v_lshl_add_u64 v[2:3], v[2:3], 0, v[4:5]
	v_lshl_add_u64 v[6:7], s[6:7], 0, v[6:7]
	v_lshlrev_b64 v[8:9], 1, v[8:9]
	s_addc_u32 s39, s39, 0
	v_lshl_add_u64 v[6:7], v[6:7], 0, v[8:9]
	global_load_dwordx4 v[96:99], v[2:3], off
	global_load_dwordx4 v[100:103], v[6:7], off
	v_ashrrev_i32_e32 v18, 3, v10
	v_mov_b64_e32 v[2:3], s[38:39]
	s_movk_i32 s2, 0x2200
	v_lshlrev_b32_e32 v10, 4, v12
	v_ashrrev_i32_e32 v19, 3, v12
	v_add_u32_e32 v130, s26, v15
	v_mad_i64_i32 v[6:7], s[40:41], v18, s2, v[2:3]
	v_and_b32_e32 v10, 0x70, v10
	v_mov_b32_e32 v11, v1
	v_mad_i64_i32 v[2:3], s[40:41], v19, s2, v[2:3]
	v_add_u32_e32 v128, s26, v14
	v_lshl_add_u64 v[134:135], v[2:3], 0, v[10:11]
	v_lshl_add_u64 v[2:3], s[38:39], 0, v[10:11]
	v_ashrrev_i32_e32 v131, 31, v130
	v_mad_i64_i32 v[136:137], s[38:39], v18, s2, v[2:3]
	v_mad_i64_i32 v[138:139], s[38:39], v19, s2, v[2:3]
	v_lshlrev_b64 v[2:3], 7, v[130:131]
	v_ashrrev_i32_e32 v129, 31, v128
	v_lshl_add_u64 v[132:133], v[6:7], 0, v[10:11]
	v_lshl_add_u64 v[2:3], s[6:7], 0, v[2:3]
	v_lshlrev_b64 v[6:7], 7, v[128:129]
	v_lshl_add_u64 v[2:3], v[2:3], 0, v[4:5]
	v_lshl_add_u64 v[6:7], s[6:7], 0, v[6:7]
	global_load_dwordx4 v[104:107], v[132:133], off offset:128
	global_load_dwordx4 v[108:111], v[134:135], off offset:128
	global_load_dwordx4 v[112:115], v[136:137], off
	global_load_dwordx4 v[116:119], v[138:139], off
	v_lshl_add_u64 v[6:7], v[6:7], 0, v[8:9]
	global_load_dwordx4 v[120:123], v[2:3], off
	global_load_dwordx4 v[124:127], v[6:7], off
	v_and_b32_e32 v2, 31, v12
	v_mul_lo_u32 v3, v14, s28
	v_mul_u32_u24_e32 v2, 0x48, v2
	v_lshl_add_u32 v129, v17, 4, v3
	v_mul_lo_u32 v3, v15, s28
	v_mad_u64_u32 v[140:141], s[38:39], v19, s28, v[10:11]
	v_mad_u64_u32 v[142:143], s[38:39], v18, s28, v[10:11]
	v_lshlrev_b32_e32 v2, 1, v2
	v_mov_b32_e32 v14, v1
	v_mov_b32_e32 v15, v1
	v_lshl_add_u32 v131, v16, 4, v3
	v_lshl_add_u64 v[148:149], s[6:7], 0, v[8:9]
	v_lshl_add_u64 v[150:151], s[6:7], 0, v[4:5]
	v_add_u32_e32 v141, v2, v0
	s_waitcnt vmcnt(13)
	v_lshlrev_b32_e32 v146, 2, v13
	v_lshl_add_u32 v143, v13, 4, v2
	v_mov_b32_e32 v0, v1
	v_mov_b32_e32 v2, v1
	v_mov_b32_e32 v3, v1
	v_mov_b32_e32 v4, v1
	v_mov_b32_e32 v5, v1
	v_mov_b32_e32 v6, v1
	v_mov_b32_e32 v7, v1
	v_mov_b32_e32 v8, v1
	v_mov_b32_e32 v9, v1
	v_mov_b32_e32 v10, v1
	v_mov_b32_e32 v12, v1
	v_mov_b32_e32 v13, v1
	v_mov_b64_e32 v[30:31], v[14:15]
	v_mov_b64_e32 v[46:47], v[14:15]
	s_mov_b32 s9, 3
	s_waitcnt vmcnt(12)
	v_mov_b32_e32 v147, 0xc47a0000
	v_mov_b32_e32 v153, 0
	s_movk_i32 s6, 0xc0
	v_mov_b64_e32 v[28:29], v[12:13]
	v_mov_b64_e32 v[26:27], v[10:11]
	v_mov_b64_e32 v[24:25], v[8:9]
	v_mov_b64_e32 v[22:23], v[6:7]
	v_mov_b64_e32 v[20:21], v[4:5]
	v_mov_b64_e32 v[18:19], v[2:3]
	v_mov_b64_e32 v[16:17], v[0:1]
	v_mov_b64_e32 v[44:45], v[12:13]
	v_mov_b64_e32 v[42:43], v[10:11]
	v_mov_b64_e32 v[40:41], v[8:9]
	v_mov_b64_e32 v[38:39], v[6:7]
	v_mov_b64_e32 v[36:37], v[4:5]
	v_mov_b64_e32 v[34:35], v[2:3]
	v_mov_b64_e32 v[32:33], v[0:1]
	v_mov_b32_e32 v204, 0x447a0000
	v_mov_b32_e32 v205, 0x447a0000
	v_mov_b32_e32 v206, 0x447a0000
	v_mov_b32_e32 v207, 0x447a0000
	v_mov_b32_e32 v208, 0x447a0000
	v_mov_b32_e32 v209, 0x447a0000
	v_mov_b32_e32 v210, 0x447a0000
	v_mov_b32_e32 v211, 0x447a0000
	v_mov_b32_e32 v212, 0x447a0000
	v_mov_b32_e32 v213, 0x447a0000
	v_mov_b32_e32 v214, 0x447a0000
	v_mov_b32_e32 v215, 0x447a0000
	v_mov_b32_e32 v216, 0x447a0000
	v_mov_b32_e32 v217, 0x447a0000
	v_mov_b32_e32 v218, 0x447a0000
	v_mov_b32_e32 v219, 0x447a0000
	s_movk_i32 s40, 0x80
	v_add_u32_e32 v2, s40, v128
	v_ashrrev_i32_e32 v3, 31, v2
	v_add_u32_e32 v4, s40, v130
	v_lshlrev_b64 v[2:3], 7, v[2:3]
	v_ashrrev_i32_e32 v5, 31, v4
	v_lshl_add_u64 v[220:221], v[148:149], 0, v[2:3]
	v_lshlrev_b64 v[4:5], 7, v[4:5]
	v_lshl_add_u64 v[222:223], v[150:151], 0, v[4:5]
	v_mov_b32_e32 v228, 0x2000
	v_mov_b32_e32 v229, 0
	s_mov_b32 s38, 0
	v_readfirstlane_b32 s42, v220
	v_readfirstlane_b32 s43, v221
	v_readfirstlane_b32 s44, v138
	v_readfirstlane_b32 s45, v139
	v_readfirstlane_b32 s46, v134
	v_readfirstlane_b32 s47, v135
	s_nop 3
	s_sub_u32 s42, s42, 0x40000000
	s_subb_u32 s43, s43, 0
	s_sub_u32 s44, s44, 0x40000000
	s_subb_u32 s45, s45, 0
	s_sub_u32 s46, s46, 0x40000000
	s_subb_u32 s47, s47, 0
	v_subrev_u32_e32 v228, s46, v134
	v_subrev_u32_e32 v229, s46, v132
	v_subrev_u32_e32 v221, s42, v222
	v_subrev_u32_e32 v220, s42, v220
	v_subrev_u32_e32 v222, s44, v138
	v_subrev_u32_e32 v223, s44, v136
	s_waitcnt vmcnt(0)
	ds_write_b128 v129, v[124:127] offset:0
	ds_write_b128 v131, v[120:123] offset:0
	ds_write_b128 v140, v[116:119] offset:9216
	ds_write_b128 v142, v[112:115] offset:9216
	s_waitcnt lgkmcnt(0)
	s_movk_i32 s40, 0x100
	s_mov_b32 s41, 0
	global_load_dwordx4 v[124:127], v220, s[42:43]
	global_load_dwordx4 v[120:123], v221, s[42:43]
	s_add_u32 s62, s44, s40
	s_addc_u32 s63, s45, 0
	global_load_dwordx4 v[116:119], v222, s[62:63]
	global_load_dwordx4 v[112:115], v223, s[62:63]
	s_add_u32 s42, s42, 0x2000
	s_addc_u32 s43, s43, 0
	s_barrier
; #define MFMA(a, b, c) __builtin_amdgcn_mfma_f32_32x32x16_f16((a), (b), (c), 0, 0, 0)
; template <int DK, bool MLA>
; DI void attn_item(const h16* __restrict__ Q, const h16* __restrict__ Kp, const h16* __restrict__ Kr, const h16* __restrict__ Vt,
;                   int kbeg, int kend, h16* __restrict__ out, h16* sm) {
;     ...
;     for (int i = 0; i < NCH; ++i) {
;       const int c = tid + 256 * i, key = c / NKC, part = c % NKC;
;       *(u32x4*)(ksm + key * KS + part * 8) = RK[i];
;     }
; #pragma unroll
;     for (int i = 0; i < 2; ++i) {
;       const int c = tid + 256 * i, dv = c >> 3, kc = c & 7;
;       *(u32x4*)(vsm + dv * 72 + kc * 8) = RV[i];
;     }
;     __syncthreads();
;     if (it + 2 < ntile) ATT_GLOAD(RK, RV, kbeg + (it + 2) * 64)
;     f32x16 st[2];
;     const float negm = -m;
; #pragma unroll
;     for (int i = 0; i < 16; ++i) { st[0][i] = negm; st[1][i] = negm; }
; #pragma unroll
;     for (int ks = 0; ks < DK / 16; ++ks) {
;       h16x8 k0 = *(const h16x8*)(ksm + r * KS + ks * 16 + hh * 8);
;       h16x8 k1 = *(const h16x8*)(ksm + (32 + r) * KS + ks * 16 + hh * 8);
;       st[0] = MFMA(k0, qf[ks], st[0]);
;       st[1] = MFMA(k1, qf[ks], st[1]);
;     }
;     float mx = fmaxf(st[0][0], st[1][0]);
; #pragma unroll
;     for (int i = 1; i < 16; ++i) mx = fmaxf(mx, fmaxf(st[0][i], st[1][i]));
;     mx = x32_max(mx);
;     if (__builtin_amdgcn_ballot_w64(mx > 8.f) != 0) {
	ds_read_b128 v[194:197], v141 offset:0
	ds_read_b128 v[198:201], v141 offset:4608
	ds_read_b128 v[230:233], v141 offset:32
	ds_read_b128 v[234:237], v141 offset:4640
	s_waitcnt lgkmcnt(3)
	v_mfma_f32_32x32x16_f16 v[48:63], v[194:197], v[80:83], v[204:219]
	ds_read_b128 v[194:197], v141 offset:64
	s_waitcnt lgkmcnt(3)
	v_mfma_f32_32x32x16_f16 v[64:79], v[198:201], v[80:83], v[204:219]
	ds_read_b128 v[198:201], v141 offset:4672
	s_waitcnt lgkmcnt(3)
	v_mfma_f32_32x32x16_f16 v[48:63], v[230:233], v[84:87], v[48:63]
	ds_read_b128 v[230:233], v141 offset:96
	s_waitcnt lgkmcnt(3)
	v_mfma_f32_32x32x16_f16 v[64:79], v[234:237], v[84:87], v[64:79]
	ds_read_b128 v[234:237], v141 offset:4704
	s_waitcnt lgkmcnt(3)
	v_mfma_f32_32x32x16_f16 v[48:63], v[194:197], v[88:91], v[48:63]
	s_waitcnt lgkmcnt(2)
	v_mfma_f32_32x32x16_f16 v[64:79], v[198:201], v[88:91], v[64:79]
	s_waitcnt lgkmcnt(1)
	v_mfma_f32_32x32x16_f16 v[48:63], v[230:233], v[92:95], v[48:63]
	s_waitcnt lgkmcnt(0)
	v_mfma_f32_32x32x16_f16 v[64:79], v[234:237], v[92:95], v[64:79]
	ds_write_b128 v129, v[100:103] offset:18432
	ds_write_b128 v131, v[96:99] offset:18432
	ds_write_b128 v140, v[108:111] offset:27648
	ds_write_b128 v142, v[104:107] offset:27648
	s_waitcnt lgkmcnt(0)
	s_movk_i32 s40, 0x180
	s_mov_b32 s41, 0
	global_load_dwordx4 v[100:103], v220, s[42:43]
	global_load_dwordx4 v[96:99], v221, s[42:43]
	s_add_u32 s62, s46, s40
	s_addc_u32 s63, s47, 0
	global_load_dwordx4 v[108:111], v228, s[62:63]
	global_load_dwordx4 v[104:107], v229, s[62:63]
	s_add_u32 s42, s42, 0x2000
	s_addc_u32 s43, s43, 0
	s_nop 7
	s_nop 7
	v_max3_f32 v0, v48, v49, v50
	v_max3_f32 v14, v51, v52, v53
	v_max3_f32 v15, v54, v55, v56
	v_max3_f32 v202, v57, v58, v59
	v_max3_f32 v0, v0, v60, v61
	v_max3_f32 v14, v14, v62, v63
	v_max3_f32 v15, v15, v64, v65
	v_max3_f32 v202, v202, v66, v67
	v_max3_f32 v0, v0, v68, v69
	v_max3_f32 v14, v14, v70, v71
	v_max3_f32 v15, v15, v72, v73
	v_max3_f32 v202, v202, v74, v75
	v_max3_f32 v0, v0, v76, v77
	v_max3_f32 v14, v14, v78, v79
	v_max3_f32 v0, v0, v14, v15
	v_max_f32_e32 v0, v0, v202
	v_mov_b32_e32 v14, v0
	s_nop 1
	v_permlane32_swap_b32_e32 v0, v14
	v_max_f32_e32 v0, v0, v14
	v_cmp_lt_f32_e32 vcc, s79, v0
	s_cbranch_vccnz .Lgq_rarepre
	s_branch .Lgq_step0

; #define MFMA(a, b, c) __builtin_amdgcn_mfma_f32_32x32x16_f16((a), (b), (c), 0, 0, 0)
; template <int DK, bool MLA>
; DI void attn_item(const h16* __restrict__ Q, const h16* __restrict__ Kp, const h16* __restrict__ Kr, const h16* __restrict__ Vt,
;                   int kbeg, int kend, h16* __restrict__ out, h16* sm) {
;     ...
; #pragma unroll
;     for (int s4 = 0; s4 < 4; ++s4) {
;       const int kt2 = s4 >> 1, hf = s4 & 1;
;       h16x8 pb;
; #pragma unroll
;       for (int j = 0; j < 8; ++j) pb[j] = (h16)st[kt2][8 * hf + j];
;       const int kb = kt2 * 32 + 16 * hf;
; #pragma unroll
;       for (int dt = 0; dt < 2; ++dt) {
;         const h16* vp = vsm + (dt * 32 + r) * 72 + kb + 4 * hh;
;         h16x4 lo = *(const h16x4*)vp, hi = *(const h16x4*)(vp + 8);
;         h16x8 va = __builtin_shufflevector(lo, hi, 0, 1, 2, 3, 4, 5, 6, 7);
;         ot[dt] = MFMA(va, pb, ot[dt]);
;       }
.Lgq_nw0:
	ds_read_b128 v[238:241], v143 offset:9216
	ds_read_b128 v[242:245], v143 offset:13824
	ds_read_b128 v[194:197], v143 offset:9248
	ds_read_b128 v[198:201], v143 offset:13856
	s_waitcnt lgkmcnt(3)
	v_mfma_f32_32x32x16_f16 v[32:47], v[238:241], v[2:5], v[32:47]
	ds_read_b128 v[238:241], v143 offset:9280
	s_add_i32 s40, s38, 4
	s_cmp_ge_u32 s40, s8
	s_cbranch_scc1 .Lgq_nl0
	s_lshl_b32 s40, s40, 7
	s_mov_b32 s41, 0
	global_load_dwordx4 v[124:127], v220, s[42:43]
	global_load_dwordx4 v[120:123], v221, s[42:43]
	s_add_u32 s62, s44, s40
	s_addc_u32 s63, s45, 0
	global_load_dwordx4 v[116:119], v222, s[62:63]
	global_load_dwordx4 v[112:115], v223, s[62:63]
	s_add_u32 s42, s42, 0x2000
	s_addc_u32 s43, s43, 0

; #define MFMA(a, b, c) __builtin_amdgcn_mfma_f32_32x32x16_f16((a), (b), (c), 0, 0, 0)
; template <int DK, bool MLA>
; DI void attn_item(const h16* __restrict__ Q, const h16* __restrict__ Kp, const h16* __restrict__ Kr, const h16* __restrict__ Vt,
;                   int kbeg, int kend, h16* __restrict__ out, h16* sm) {
;     ...
; #pragma unroll
;     for (int s4 = 0; s4 < 4; ++s4) {
;       const int kt2 = s4 >> 1, hf = s4 & 1;
;       h16x8 pb;
; #pragma unroll
;       for (int j = 0; j < 8; ++j) pb[j] = (h16)st[kt2][8 * hf + j];
;       const int kb = kt2 * 32 + 16 * hf;
; #pragma unroll
;       for (int dt = 0; dt < 2; ++dt) {
;         const h16* vp = vsm + (dt * 32 + r) * 72 + kb + 4 * hh;
;         h16x4 lo = *(const h16x4*)vp, hi = *(const h16x4*)(vp + 8);
;         h16x8 va = __builtin_shufflevector(lo, hi, 0, 1, 2, 3, 4, 5, 6, 7);
;         ot[dt] = MFMA(va, pb, ot[dt]);
;       }
.Lgq_nw1:
	ds_read_b128 v[238:241], v143 offset:27648
	ds_read_b128 v[242:245], v143 offset:32256
	ds_read_b128 v[194:197], v143 offset:27680
	ds_read_b128 v[198:201], v143 offset:32288
	s_waitcnt lgkmcnt(3)
	v_mfma_f32_32x32x16_f16 v[32:47], v[238:241], v[2:5], v[32:47]
	ds_read_b128 v[238:241], v143 offset:27712
	s_add_i32 s40, s38, 4
	s_cmp_ge_u32 s40, s8
	s_cbranch_scc1 .Lgq_nl1
	s_lshl_b32 s40, s40, 7
	s_mov_b32 s41, 0
	global_load_dwordx4 v[100:103], v220, s[42:43]
	global_load_dwordx4 v[96:99], v221, s[42:43]
	s_add_u32 s62, s46, s40
	s_addc_u32 s63, s47, 0
	global_load_dwordx4 v[108:111], v228, s[62:63]
	global_load_dwordx4 v[104:107], v229, s[62:63]
	s_add_u32 s42, s42, 0x2000
	s_addc_u32 s43, s43, 0

; #define MFMA(a, b, c) __builtin_amdgcn_mfma_f32_32x32x16_f16((a), (b), (c), 0, 0, 0)
; template <int DK, bool MLA>
; DI void attn_item(const h16* __restrict__ Q, const h16* __restrict__ Kp, const h16* __restrict__ Kr, const h16* __restrict__ Vt,
;                   int kbeg, int kend, h16* __restrict__ out, h16* sm) {
;     ...
; #pragma unroll
;     for (int s4 = 0; s4 < 4; ++s4) {
;       const int kt2 = s4 >> 1, hf = s4 & 1;
;       h16x8 pb;
; #pragma unroll
;       for (int j = 0; j < 8; ++j) pb[j] = (h16)st[kt2][8 * hf + j];
;       const int kb = kt2 * 32 + 16 * hf;
; #pragma unroll
;       for (int dt = 0; dt < 2; ++dt) {
;         const h16* vp = vsm + (dt * 32 + r) * 72 + kb + 4 * hh;
;         h16x4 lo = *(const h16x4*)vp, hi = *(const h16x4*)(vp + 8);
;         h16x8 va = __builtin_shufflevector(lo, hi, 0, 1, 2, 3, 4, 5, 6, 7);
;         ot[dt] = MFMA(va, pb, ot[dt]);
;       }
.Lgq_nw2:
	ds_read_b128 v[238:241], v143 offset:46080
	ds_read_b128 v[242:245], v143 offset:50688
	ds_read_b128 v[194:197], v143 offset:46112
	ds_read_b128 v[198:201], v143 offset:50720
	s_waitcnt lgkmcnt(3)
	v_mfma_f32_32x32x16_f16 v[32:47], v[238:241], v[2:5], v[32:47]
	ds_read_b128 v[238:241], v143 offset:46144
	s_add_i32 s40, s38, 4
	s_cmp_ge_u32 s40, s8
	s_cbranch_scc1 .Lgq_nl2
	s_lshl_b32 s40, s40, 7
	s_mov_b32 s41, 0
	global_load_dwordx4 v[124:127], v220, s[42:43]
	global_load_dwordx4 v[120:123], v221, s[42:43]
	s_add_u32 s62, s44, s40
	s_addc_u32 s63, s45, 0
	global_load_dwordx4 v[116:119], v222, s[62:63]
	global_load_dwordx4 v[112:115], v223, s[62:63]
	s_add_u32 s42, s42, 0x2000
	s_addc_u32 s43, s43, 0

; #define MFMA(a, b, c) __builtin_amdgcn_mfma_f32_32x32x16_f16((a), (b), (c), 0, 0, 0)
; template <int DK, bool MLA>
; DI void attn_item(const h16* __restrict__ Q, const h16* __restrict__ Kp, const h16* __restrict__ Kr, const h16* __restrict__ Vt,
;                   int kbeg, int kend, h16* __restrict__ out, h16* sm) {
;     ...
; #pragma unroll
;     for (int s4 = 0; s4 < 4; ++s4) {
;       const int kt2 = s4 >> 1, hf = s4 & 1;
;       h16x8 pb;
; #pragma unroll
;       for (int j = 0; j < 8; ++j) pb[j] = (h16)st[kt2][8 * hf + j];
;       const int kb = kt2 * 32 + 16 * hf;
; #pragma unroll
;       for (int dt = 0; dt < 2; ++dt) {
;         const h16* vp = vsm + (dt * 32 + r) * 72 + kb + 4 * hh;
;         h16x4 lo = *(const h16x4*)vp, hi = *(const h16x4*)(vp + 8);
;         h16x8 va = __builtin_shufflevector(lo, hi, 0, 1, 2, 3, 4, 5, 6, 7);
;         ot[dt] = MFMA(va, pb, ot[dt]);
;       }
.Lgq_nw3:
	ds_read_b128 v[238:241], v143 offset:9216
	ds_read_b128 v[242:245], v143 offset:13824
	ds_read_b128 v[194:197], v143 offset:9248
	ds_read_b128 v[198:201], v143 offset:13856
	s_waitcnt lgkmcnt(3)
	v_mfma_f32_32x32x16_f16 v[32:47], v[238:241], v[2:5], v[32:47]
	ds_read_b128 v[238:241], v143 offset:9280
	s_add_i32 s40, s38, 4
	s_cmp_ge_u32 s40, s8
	s_cbranch_scc1 .Lgq_nl3
	s_lshl_b32 s40, s40, 7
	s_mov_b32 s41, 0
	global_load_dwordx4 v[100:103], v220, s[42:43]
	global_load_dwordx4 v[96:99], v221, s[42:43]
	s_add_u32 s62, s46, s40
	s_addc_u32 s63, s47, 0
	global_load_dwordx4 v[108:111], v228, s[62:63]
	global_load_dwordx4 v[104:107], v229, s[62:63]
	s_add_u32 s42, s42, 0x2000
	s_addc_u32 s43, s43, 0

; #define MFMA(a, b, c) __builtin_amdgcn_mfma_f32_32x32x16_f16((a), (b), (c), 0, 0, 0)
; template <int DK, bool MLA>
; DI void attn_item(const h16* __restrict__ Q, const h16* __restrict__ Kp, const h16* __restrict__ Kr, const h16* __restrict__ Vt,
;                   int kbeg, int kend, h16* __restrict__ out, h16* sm) {
;     ...
; #pragma unroll
;     for (int s4 = 0; s4 < 4; ++s4) {
;       const int kt2 = s4 >> 1, hf = s4 & 1;
;       h16x8 pb;
; #pragma unroll
;       for (int j = 0; j < 8; ++j) pb[j] = (h16)st[kt2][8 * hf + j];
;       const int kb = kt2 * 32 + 16 * hf;
; #pragma unroll
;       for (int dt = 0; dt < 2; ++dt) {
;         const h16* vp = vsm + (dt * 32 + r) * 72 + kb + 4 * hh;
;         h16x4 lo = *(const h16x4*)vp, hi = *(const h16x4*)(vp + 8);
;         h16x8 va = __builtin_shufflevector(lo, hi, 0, 1, 2, 3, 4, 5, 6, 7);
;         ot[dt] = MFMA(va, pb, ot[dt]);
;       }
.Lgq_nw4:
	ds_read_b128 v[238:241], v143 offset:27648
	ds_read_b128 v[242:245], v143 offset:32256
	ds_read_b128 v[194:197], v143 offset:27680
	ds_read_b128 v[198:201], v143 offset:32288
	s_waitcnt lgkmcnt(3)
	v_mfma_f32_32x32x16_f16 v[32:47], v[238:241], v[2:5], v[32:47]
	ds_read_b128 v[238:241], v143 offset:27712
	s_add_i32 s40, s38, 4
	s_cmp_ge_u32 s40, s8
	s_cbranch_scc1 .Lgq_nl4
	s_lshl_b32 s40, s40, 7
	s_mov_b32 s41, 0
	global_load_dwordx4 v[124:127], v220, s[42:43]
	global_load_dwordx4 v[120:123], v221, s[42:43]
	s_add_u32 s62, s44, s40
	s_addc_u32 s63, s45, 0
	global_load_dwordx4 v[116:119], v222, s[62:63]
	global_load_dwordx4 v[112:115], v223, s[62:63]
	s_add_u32 s42, s42, 0x2000
	s_addc_u32 s43, s43, 0

; #define MFMA(a, b, c) __builtin_amdgcn_mfma_f32_32x32x16_f16((a), (b), (c), 0, 0, 0)
; template <int DK, bool MLA>
; DI void attn_item(const h16* __restrict__ Q, const h16* __restrict__ Kp, const h16* __restrict__ Kr, const h16* __restrict__ Vt,
;                   int kbeg, int kend, h16* __restrict__ out, h16* sm) {
;     ...
; #pragma unroll
;     for (int s4 = 0; s4 < 4; ++s4) {
;       const int kt2 = s4 >> 1, hf = s4 & 1;
;       h16x8 pb;
; #pragma unroll
;       for (int j = 0; j < 8; ++j) pb[j] = (h16)st[kt2][8 * hf + j];
;       const int kb = kt2 * 32 + 16 * hf;
; #pragma unroll
;       for (int dt = 0; dt < 2; ++dt) {
;         const h16* vp = vsm + (dt * 32 + r) * 72 + kb + 4 * hh;
;         h16x4 lo = *(const h16x4*)vp, hi = *(const h16x4*)(vp + 8);
;         h16x8 va = __builtin_shufflevector(lo, hi, 0, 1, 2, 3, 4, 5, 6, 7);
;         ot[dt] = MFMA(va, pb, ot[dt]);
;       }
.Lgq_nw5:
	ds_read_b128 v[238:241], v143 offset:46080
	ds_read_b128 v[242:245], v143 offset:50688
	ds_read_b128 v[194:197], v143 offset:46112
	ds_read_b128 v[198:201], v143 offset:50720
	s_waitcnt lgkmcnt(3)
	v_mfma_f32_32x32x16_f16 v[32:47], v[238:241], v[2:5], v[32:47]
	ds_read_b128 v[238:241], v143 offset:46144
	s_add_i32 s40, s38, 4
	s_cmp_ge_u32 s40, s8
	s_cbranch_scc1 .Lgq_nl5
	s_lshl_b32 s40, s40, 7
	s_mov_b32 s41, 0
	global_load_dwordx4 v[100:103], v220, s[42:43]
	global_load_dwordx4 v[96:99], v221, s[42:43]
	s_add_u32 s62, s46, s40
	s_addc_u32 s63, s47, 0
	global_load_dwordx4 v[108:111], v228, s[62:63]
	global_load_dwordx4 v[104:107], v229, s[62:63]
	s_add_u32 s42, s42, 0x2000
	s_addc_u32 s43, s43, 0
